# in-proj work-queue mapping NP 4->1 (all 12 column tiles of a 256-row panel inside one XCD) on top of v62
# speedup vs baseline: 1.0140x; 1.0019x over previous
.LBB0_121:
	s_andn2_saveexec_b64 s[48:49], s[48:49]
	s_cbranch_execz .LBB0_112
	s_mov_b32 s25, 0x55555556
	v_mul_hi_i32 v2, v0, s25
	v_lshrrev_b32_e32 v2, 2, v2
	s_movk_i32 s25, 18
	v_mad_u32_u24 v4, v16, s25, v2
	v_mul_u32_u24_e32 v2, 12, v2
	v_sub_u32_e32 v0, v0, v2
	v_lshl_or_b32 v1, v4, 6, v0
	s_andn2_b64 s[46:47], s[46:47], exec
	s_branch .LBB0_112
